# prep U-row loop: loop-invariant norm_pre loaded once into spare VGPRs, per-chunk load+vmcnt(0) (which also waited on the previous store) removed
# speedup vs baseline: 1.0388x; 1.0040x over previous
.LBB0_7:
	v_lshl_add_u32 v136, s57, 3, v6
	s_mov_b32 s2, 0x8900
	v_cmp_gt_i32_e32 vcc, s2, v136
	v_lshlrev_b32_e32 v140, 4, v138
	v_mbcnt_lo_u32_b32 v129, -1, 0
	s_and_saveexec_b64 s[6:7], vcc
	s_cbranch_execz .LBB0_22
	v_or_b32_e32 v16, 0x100, v138
	v_mov_b32_e32 v3, 0
	v_or_b32_e32 v18, 0x140, v138
	v_lshlrev_b32_e32 v2, 4, v16
	v_or_b32_e32 v20, 0x180, v138
	v_lshl_add_u64 v[6:7], s[48:49], 0, v[2:3]
	v_lshlrev_b32_e32 v2, 4, v18
	v_or_b32_e32 v22, 0x1c0, v138
	v_lshl_add_u64 v[8:9], s[48:49], 0, v[2:3]
	v_lshlrev_b32_e32 v2, 4, v20
	v_mbcnt_hi_u32_b32 v35, -1, v129
	v_mov_b32_e32 v141, v3
	v_lshl_add_u64 v[10:11], s[48:49], 0, v[2:3]
	v_lshlrev_b32_e32 v2, 4, v22
	v_and_b32_e32 v17, 64, v35
	s_lshl_b32 s2, s3, 3
	v_lshl_add_u64 v[4:5], s[48:49], 0, v[140:141]
	v_lshl_add_u64 v[12:13], s[48:49], 0, v[2:3]
	s_mov_b64 s[8:9], 0
	s_movk_i32 s18, 0x1080
	v_mov_b64_e32 v[14:15], s[70:71]
	s_mov_b32 s19, 0x8820
	s_mov_b32 s20, 0x801f
	s_mov_b32 s21, 0x7fe007ff
	s_movk_i32 s22, 0xbff0
	v_lshlrev_b32_e32 v16, 4, v16
	v_lshlrev_b32_e32 v18, 4, v18
	v_lshlrev_b32_e32 v20, 4, v20
	v_lshlrev_b32_e32 v22, 4, v22
	s_mov_b32 s10, 0
	v_mov_b32_e32 v34, 0x358637bd
	s_mov_b32 s23, 0x800000
	s_mov_b32 s24, 0x88ff
	v_lshlrev_b32_e32 v2, 4, v138
	v_xor_b32_e32 v36, 16, v35
	v_add_u32_e32 v37, 64, v17
	v_xor_b32_e32 v38, 32, v35
	v_lshlrev_b32_e32 v24, 3, v138
	v_mov_b32_e32 v39, v136
	global_load_dwordx4 v[182:185], v[4:5], off
	global_load_dwordx4 v[186:189], v[4:5], off offset:1024
	global_load_dwordx4 v[190:193], v[4:5], off offset:2048
	global_load_dwordx4 v[194:197], v[4:5], off offset:3072
	global_load_dwordx4 v[198:201], v[6:7], off
	global_load_dwordx4 v[202:205], v[8:9], off
	global_load_dwordx4 v[206:209], v[10:11], off
	global_load_dwordx4 v[210:213], v[12:13], off
	s_waitcnt vmcnt(0)
	s_branch .LBB0_10

.LBB0_19:
	s_or_b64 exec, exec, s[14:15]
	v_lshlrev_b64 v[28:29], 13, v[28:29]
	v_lshl_add_u64 v[32:33], v[30:31], 0, v[28:29]
	v_lshl_add_u64 v[48:49], v[32:33], 0, v[2:3]
	global_load_dwordx4 v[28:31], v[48:49], off
	global_load_dwordx4 v[40:43], v[48:49], off offset:1024
	v_mov_b32_e32 v17, v3
	v_mov_b32_e32 v19, v3
	global_load_dwordx4 v[44:47], v[48:49], off offset:2048
	v_lshl_add_u64 v[52:53], v[32:33], 0, v[16:17]
	v_lshl_add_u64 v[56:57], v[32:33], 0, v[18:19]
	global_load_dwordx4 v[48:51], v[48:49], off offset:3072
	s_nop 0
	global_load_dwordx4 v[52:55], v[52:53], off
	s_nop 0
	global_load_dwordx4 v[56:59], v[56:57], off
	v_mov_b32_e32 v21, v3
	v_mov_b32_e32 v23, v3
	v_lshl_add_u64 v[60:61], v[32:33], 0, v[20:21]
	v_lshl_add_u64 v[32:33], v[32:33], 0, v[22:23]
	global_load_dwordx4 v[60:63], v[60:61], off
	s_nop 0
	global_load_dwordx4 v[64:67], v[32:33], off
	v_cmp_lt_i32_e32 vcc, v36, v37
	s_waitcnt vmcnt(7)
	v_pk_mul_f32 v[72:73], v[28:29], v[28:29]
	s_waitcnt vmcnt(6)
	v_pk_mul_f32 v[76:77], v[40:41], v[40:41]
	v_pk_mul_f32 v[32:33], v[30:31], v[30:31]
	v_pk_mul_f32 v[74:75], v[42:43], v[42:43]
	s_waitcnt vmcnt(5)
	v_pk_mul_f32 v[80:81], v[44:45], v[44:45]
	v_add_f32_e32 v19, v76, v77
	v_add_f32_e32 v21, v72, v73
	v_pk_mul_f32 v[78:79], v[46:47], v[46:47]
	s_waitcnt vmcnt(4)
	v_pk_mul_f32 v[84:85], v[48:49], v[48:49]
	s_waitcnt vmcnt(3)
	v_mov_b32_e32 v92, v53
	s_waitcnt vmcnt(2)
	v_mov_b32_e32 v93, v57
	v_add_f32_e32 v23, v80, v81
	v_add_f32_e32 v19, v19, v74
	v_add_f32_e32 v21, v21, v32
	v_pk_mul_f32 v[82:83], v[50:51], v[50:51]
	v_mov_b32_e32 v90, v52
	v_mov_b32_e32 v91, v56
	v_pk_mul_f32 v[92:93], v[92:93], v[92:93]
	v_add_f32_e32 v25, v84, v85
	v_add_f32_e32 v23, v23, v78
	v_add_f32_e32 v19, v19, v75
	v_add_f32_e32 v21, v21, v33
	v_mov_b32_e32 v86, v54
	v_mov_b32_e32 v87, v58
	s_waitcnt vmcnt(1)
	v_mov_b32_e32 v100, v61
	s_waitcnt vmcnt(0)
	v_mov_b32_e32 v101, v65
	v_pk_fma_f32 v[72:73], v[90:91], v[90:91], v[92:93]
	v_add_f32_e32 v25, v25, v82
	v_add_f32_e32 v23, v23, v79
	v_add_f32_e32 v19, v21, v19
	v_mov_b32_e32 v88, v55
	v_mov_b32_e32 v89, v59
	v_mov_b32_e32 v98, v60
	v_mov_b32_e32 v99, v64
	v_pk_mul_f32 v[100:101], v[100:101], v[100:101]
	v_pk_fma_f32 v[72:73], v[86:87], v[86:87], v[72:73]
	v_add_f32_e32 v25, v25, v83
	v_add_f32_e32 v19, v19, v23
	v_mov_b32_e32 v94, v62
	v_mov_b32_e32 v95, v66
	v_pk_fma_f32 v[76:77], v[98:99], v[98:99], v[100:101]
	v_pk_fma_f32 v[32:33], v[88:89], v[88:89], v[72:73]
	v_add_f32_e32 v19, v19, v25
	v_mov_b32_e32 v96, v63
	v_mov_b32_e32 v97, v67
	v_pk_fma_f32 v[76:77], v[94:95], v[94:95], v[76:77]
	v_add_f32_e32 v19, v19, v32
	v_pk_fma_f32 v[72:73], v[96:97], v[96:97], v[76:77]
	v_add_f32_e32 v19, v19, v33
	v_add_f32_e32 v19, v19, v72
	v_add_f32_e32 v19, v19, v73
	v_cndmask_b32_e32 v17, v35, v36, vcc
	v_lshlrev_b32_e32 v17, 2, v17
	v_add_f32_dpp v19, v19, v19 quad_perm:[1,0,3,2] row_mask:0xf bank_mask:0xf bound_ctrl:1
	v_cmp_lt_i32_e32 vcc, v38, v37
	v_mov_b32_e32 v25, v3
	v_add_f32_dpp v19, v19, v19 quad_perm:[2,3,0,1] row_mask:0xf bank_mask:0xf bound_ctrl:1
	v_cndmask_b32_e32 v21, v35, v38, vcc
	v_lshlrev_b32_e32 v21, 2, v21
	v_add_f32_dpp v19, v19, v19 row_half_mirror row_mask:0xf bank_mask:0xf bound_ctrl:1
	v_lshl_add_u64 v[32:33], v[26:27], 0, v[24:25]
	s_nop 0
	v_add_f32_dpp v19, v19, v19 row_mirror row_mask:0xf bank_mask:0xf bound_ctrl:1
	ds_bpermute_b32 v17, v17, v19
	s_waitcnt lgkmcnt(0)
	v_add_f32_e32 v17, v19, v17
	ds_bpermute_b32 v19, v21, v17
	s_waitcnt lgkmcnt(0)
	v_add_f32_e32 v17, v17, v19
	v_fmamk_f32 v17, v17, 0x3a000000, v34
	v_mul_f32_e32 v19, 0x4b800000, v17
	v_cmp_gt_f32_e32 vcc, s23, v17
	s_nop 1
	v_cndmask_b32_e32 v17, v17, v19, vcc
	v_rsq_f32_e32 v17, v17
	s_nop 0
	v_mul_f32_e32 v19, 0x45800000, v17
	v_cndmask_b32_e32 v72, v17, v19, vcc
	v_pk_mul_f32 v[26:27], v[28:29], v[72:73] op_sel_hi:[1,0]
	v_pk_mul_f32 v[28:29], v[30:31], v[72:73] op_sel_hi:[1,0]
	v_pk_mul_f32 v[26:27], v[182:183], v[26:27]
	v_pk_mul_f32 v[28:29], v[184:185], v[28:29]
	v_cvt_pk_bf16_f32 v26, v26, v27
	v_cvt_pk_bf16_f32 v27, v28, v29
	global_store_dwordx2 v[32:33], v[26:27], off
	v_pk_mul_f32 v[30:31], v[40:41], v[72:73] op_sel_hi:[1,0]
	v_pk_mul_f32 v[40:41], v[42:43], v[72:73] op_sel_hi:[1,0]
	v_pk_mul_f32 v[26:27], v[186:187], v[30:31]
	v_pk_mul_f32 v[28:29], v[188:189], v[40:41]
	v_cvt_pk_bf16_f32 v26, v26, v27
	v_cvt_pk_bf16_f32 v27, v28, v29
	global_store_dwordx2 v[32:33], v[26:27], off offset:512
	v_pk_mul_f32 v[30:31], v[44:45], v[72:73] op_sel_hi:[1,0]
	v_pk_mul_f32 v[40:41], v[46:47], v[72:73] op_sel_hi:[1,0]
	v_pk_mul_f32 v[26:27], v[30:31], v[190:191]
	v_pk_mul_f32 v[28:29], v[40:41], v[192:193]
	v_cvt_pk_bf16_f32 v26, v26, v27
	v_cvt_pk_bf16_f32 v27, v28, v29
	global_store_dwordx2 v[32:33], v[26:27], off offset:1024
	v_pk_mul_f32 v[30:31], v[48:49], v[72:73] op_sel_hi:[1,0]
	v_pk_mul_f32 v[40:41], v[50:51], v[72:73] op_sel_hi:[1,0]
	v_pk_mul_f32 v[26:27], v[30:31], v[194:195]
	v_pk_mul_f32 v[28:29], v[40:41], v[196:197]
	v_cvt_pk_bf16_f32 v26, v26, v27
	v_cvt_pk_bf16_f32 v27, v28, v29
	global_store_dwordx2 v[32:33], v[26:27], off offset:1536
	v_pk_mul_f32 v[30:31], v[52:53], v[72:73] op_sel_hi:[1,0]
	v_pk_mul_f32 v[40:41], v[54:55], v[72:73] op_sel_hi:[1,0]
	v_pk_mul_f32 v[26:27], v[30:31], v[198:199]
	v_pk_mul_f32 v[28:29], v[40:41], v[200:201]
	v_cvt_pk_bf16_f32 v26, v26, v27
	v_cvt_pk_bf16_f32 v27, v28, v29
	global_store_dwordx2 v[32:33], v[26:27], off offset:2048
	v_pk_mul_f32 v[30:31], v[56:57], v[72:73] op_sel_hi:[1,0]
	v_pk_mul_f32 v[40:41], v[58:59], v[72:73] op_sel_hi:[1,0]
	v_pk_mul_f32 v[26:27], v[30:31], v[202:203]
	v_pk_mul_f32 v[28:29], v[40:41], v[204:205]
	v_cvt_pk_bf16_f32 v26, v26, v27
	v_cvt_pk_bf16_f32 v27, v28, v29
	global_store_dwordx2 v[32:33], v[26:27], off offset:2560
	v_pk_mul_f32 v[30:31], v[60:61], v[72:73] op_sel_hi:[1,0]
	v_pk_mul_f32 v[40:41], v[62:63], v[72:73] op_sel_hi:[1,0]
	v_pk_mul_f32 v[26:27], v[30:31], v[206:207]
	v_pk_mul_f32 v[28:29], v[40:41], v[208:209]
	v_cvt_pk_bf16_f32 v26, v26, v27
	v_cvt_pk_bf16_f32 v27, v28, v29
	global_store_dwordx2 v[32:33], v[26:27], off offset:3072
	v_pk_mul_f32 v[30:31], v[64:65], v[72:73] op_sel_hi:[1,0]
	v_pk_mul_f32 v[40:41], v[66:67], v[72:73] op_sel_hi:[1,0]
	v_pk_mul_f32 v[26:27], v[30:31], v[210:211]
	v_pk_mul_f32 v[28:29], v[40:41], v[212:213]
	v_cvt_pk_bf16_f32 v26, v26, v27
	v_cvt_pk_bf16_f32 v27, v28, v29
	global_store_dwordx2 v[32:33], v[26:27], off offset:3584
